# rwkv_post scratch prefetch two tokens ahead (on top of the prep_x/final_norm row prefetch)
# speedup vs baseline: 1.0004x; 1.0004x over previous
.LBB0_1148:
	s_ashr_i32 s4, s2, 2
	s_ashr_i32 s5, s2, 31
	s_lshr_b32 s6, s5, 19
	s_ashr_i32 s5, s4, 31
	s_add_i32 s8, s4, s6
	s_lshl_b64 s[6:7], s[4:5], 8
	v_mov_b32_e32 v29, s7
	v_or_b32_e32 v28, s6, v0
	s_and_b32 s20, s4, 0x1fff
	s_lshl_b64 s[4:5], s[4:5], 11
	s_ashr_i32 s8, s8, 13
	v_mov_b32_e32 v31, s7
	v_or_b32_e32 v30, s6, v2
	v_mov_b32_e32 v33, s7
	v_or_b32_e32 v32, s6, v4
	v_mov_b32_e32 v35, s7
	v_or_b32_e32 v34, s6, v6
	v_lshl_add_u64 v[36:37], v[28:29], 2, s[12:13]
	v_lshl_add_u64 v[14:15], v[10:11], 0, s[4:5]
	s_lshl_b32 s4, s8, 2
	v_lshl_add_u64 v[28:29], v[28:29], 1, s[14:15]
	v_lshl_add_u64 v[38:39], v[30:31], 2, s[12:13]
	v_lshl_add_u64 v[30:31], v[30:31], 1, s[14:15]
	v_lshl_add_u64 v[40:41], v[32:33], 2, s[12:13]
	v_lshl_add_u64 v[32:33], v[32:33], 1, s[14:15]
	v_lshl_add_u64 v[42:43], v[34:35], 2, s[12:13]
	v_lshl_add_u64 v[34:35], v[34:35], 1, s[14:15]
	global_load_dword v45, v[36:37], off
	global_load_ushort v27, v[28:29], off
	global_load_dword v44, v[38:39], off
	global_load_ushort v48, v[30:31], off
	global_load_dword v47, v[40:41], off
	global_load_ushort v49, v[32:33], off
	global_load_dword v46, v[42:43], off
	global_load_ushort v50, v[34:35], off
	s_ashr_i32 s5, s4, 31
	s_or_b32 s6, s4, 1
	s_or_b32 s8, s4, 2
	s_or_b32 s18, s4, 3
	s_lshl_b64 s[4:5], s[4:5], 13
	s_ashr_i32 s7, s6, 31
	s_ashr_i32 s9, s8, 31
	s_ashr_i32 s19, s18, 31
	s_or_b32 s21, s4, s20
	s_mul_i32 s22, s5, 0x380
	s_lshl_b64 s[4:5], s[6:7], 13
	s_lshl_b64 s[6:7], s[8:9], 13
	s_lshl_b64 s[8:9], s[18:19], 13
	v_mad_u64_u32 v[28:29], s[18:19], s21, v26, v[8:9]
	v_add_u32_e32 v29, s22, v29
	global_load_ushort v36, v[28:29], off offset:256
	global_load_ushort v37, v[28:29], off offset:384
	global_load_ushort v40, v[28:29], off offset:512
	s_or_b32 s4, s4, s20
	s_mul_i32 s18, s5, 0x380
	s_or_b32 s6, s6, s20
	s_or_b32 s8, s8, s20
	v_mad_u64_u32 v[30:31], s[4:5], s4, v26, v[8:9]
	s_mulk_i32 s7, 0x380
	s_mulk_i32 s9, 0x380
	v_mad_u64_u32 v[32:33], s[4:5], s6, v26, v[8:9]
	v_mad_u64_u32 v[34:35], s[4:5], s8, v26, v[8:9]
	v_add_u32_e32 v31, s18, v31
	v_add_u32_e32 v33, s7, v33
	v_add_u32_e32 v35, s9, v35
	global_load_ushort v38, v[30:31], off offset:256
	global_load_ushort v39, v[30:31], off offset:384
	global_load_ushort v41, v[32:33], off offset:256
	global_load_ushort v42, v[32:33], off offset:384
	global_load_ushort v43, v[34:35], off offset:256
	global_load_ushort v51, v[34:35], off offset:384
	global_load_ushort v52, v[30:31], off offset:512
	global_load_ushort v53, v[32:33], off offset:512
	global_load_ushort v54, v[34:35], off offset:512
	s_lshl_b32 s35, s1, 1
	s_add_i32 s35, s35, s2
	s_cmp_lt_i32 s35, 0x10000
	s_cselect_b32 s35, s35, s2
	s_ashr_i32 s24, s35, 2
	s_ashr_i32 s25, s35, 31
	s_lshr_b32 s26, s25, 19
	s_ashr_i32 s25, s24, 31
	s_add_i32 s28, s24, s26
	s_lshl_b64 s[26:27], s[24:25], 8
	v_mov_b32_e32 v61, s27
	v_or_b32_e32 v60, s26, v0
	s_and_b32 s32, s24, 0x1fff
	s_lshl_b64 s[24:25], s[24:25], 11
	s_ashr_i32 s28, s28, 13
	v_mov_b32_e32 v63, s27
	v_or_b32_e32 v62, s26, v2
	v_mov_b32_e32 v65, s27
	v_or_b32_e32 v64, s26, v4
	v_mov_b32_e32 v67, s27
	v_or_b32_e32 v66, s26, v6
	v_lshl_add_u64 v[68:69], v[60:61], 2, s[12:13]
	s_lshl_b32 s24, s28, 2
	v_lshl_add_u64 v[60:61], v[60:61], 1, s[14:15]
	v_lshl_add_u64 v[70:71], v[62:63], 2, s[12:13]
	v_lshl_add_u64 v[62:63], v[62:63], 1, s[14:15]
	v_lshl_add_u64 v[72:73], v[64:65], 2, s[12:13]
	v_lshl_add_u64 v[64:65], v[64:65], 1, s[14:15]
	v_lshl_add_u64 v[74:75], v[66:67], 2, s[12:13]
	v_lshl_add_u64 v[66:67], v[66:67], 1, s[14:15]
	global_load_dword v76, v[68:69], off
	global_load_ushort v76, v[60:61], off
	global_load_dword v76, v[70:71], off
	global_load_ushort v76, v[62:63], off
	global_load_dword v76, v[72:73], off
	global_load_ushort v76, v[64:65], off
	global_load_dword v76, v[74:75], off
	global_load_ushort v76, v[66:67], off
	s_ashr_i32 s25, s24, 31
	s_or_b32 s26, s24, 1
	s_or_b32 s28, s24, 2
	s_or_b32 s30, s24, 3
	s_lshl_b64 s[24:25], s[24:25], 13
	s_ashr_i32 s27, s26, 31
	s_ashr_i32 s29, s28, 31
	s_ashr_i32 s31, s30, 31
	s_or_b32 s33, s24, s32
	s_mul_i32 s34, s25, 0x380
	s_lshl_b64 s[24:25], s[26:27], 13
	s_lshl_b64 s[26:27], s[28:29], 13
	s_lshl_b64 s[28:29], s[30:31], 13
	v_mad_u64_u32 v[60:61], s[30:31], s33, v26, v[8:9]
	v_add_u32_e32 v61, s34, v61
	global_load_ushort v76, v[60:61], off offset:256
	global_load_ushort v76, v[60:61], off offset:384
	global_load_ushort v76, v[60:61], off offset:512
	s_or_b32 s24, s24, s32
	s_mul_i32 s30, s25, 0x380
	s_or_b32 s26, s26, s32
	s_or_b32 s28, s28, s32
	v_mad_u64_u32 v[62:63], s[24:25], s24, v26, v[8:9]
	s_mulk_i32 s27, 0x380
	s_mulk_i32 s29, 0x380
	v_mad_u64_u32 v[64:65], s[24:25], s26, v26, v[8:9]
	v_mad_u64_u32 v[66:67], s[24:25], s28, v26, v[8:9]
	v_add_u32_e32 v63, s30, v63
	v_add_u32_e32 v65, s27, v65
	v_add_u32_e32 v67, s29, v67
	global_load_ushort v76, v[62:63], off offset:256
	global_load_ushort v76, v[62:63], off offset:384
	global_load_ushort v76, v[64:65], off offset:256
	global_load_ushort v76, v[64:65], off offset:384
	global_load_ushort v76, v[66:67], off offset:256
	global_load_ushort v76, v[66:67], off offset:384
	global_load_ushort v76, v[62:63], off offset:512
	global_load_ushort v76, v[64:65], off offset:512
	global_load_ushort v76, v[66:67], off offset:512
	s_add_i32 s2, s2, s1
	s_cmp_lt_i32 s2, 0x10000
	s_waitcnt vmcnt(39)
	v_mov_b32_dpp v29, v45 quad_perm:[1,0,3,2] row_mask:0xf bank_mask:0xf bound_ctrl:1
	s_waitcnt vmcnt(38)
	v_cvt_f32_f16_e32 v27, v27
	s_waitcnt vmcnt(37)
	v_mov_b32_dpp v28, v44 quad_perm:[1,0,3,2] row_mask:0xf bank_mask:0xf bound_ctrl:1
	v_pk_add_f32 v[28:29], v[44:45], v[28:29]
	s_waitcnt vmcnt(35)
	v_mov_b32_dpp v31, v47 quad_perm:[1,0,3,2] row_mask:0xf bank_mask:0xf bound_ctrl:1
	v_cvt_f32_f16_e32 v48, v48
	s_waitcnt vmcnt(33)
	v_mov_b32_dpp v30, v46 quad_perm:[1,0,3,2] row_mask:0xf bank_mask:0xf bound_ctrl:1
	v_pk_add_f32 v[30:31], v[46:47], v[30:31]
	v_mov_b32_dpp v33, v29 quad_perm:[2,3,0,1] row_mask:0xf bank_mask:0xf bound_ctrl:1
	v_mov_b32_dpp v32, v28 quad_perm:[2,3,0,1] row_mask:0xf bank_mask:0xf bound_ctrl:1
	v_mov_b32_dpp v35, v31 quad_perm:[2,3,0,1] row_mask:0xf bank_mask:0xf bound_ctrl:1
	v_mov_b32_dpp v34, v30 quad_perm:[2,3,0,1] row_mask:0xf bank_mask:0xf bound_ctrl:1
	v_pk_add_f32 v[28:29], v[28:29], v[32:33]
	v_pk_add_f32 v[30:31], v[30:31], v[34:35]
	v_cvt_f32_f16_e32 v49, v49
	v_mov_b32_dpp v33, v29 row_half_mirror row_mask:0xf bank_mask:0xf bound_ctrl:1
	v_mov_b32_dpp v32, v28 row_half_mirror row_mask:0xf bank_mask:0xf bound_ctrl:1
	v_mov_b32_dpp v35, v31 row_half_mirror row_mask:0xf bank_mask:0xf bound_ctrl:1
	v_mov_b32_dpp v34, v30 row_half_mirror row_mask:0xf bank_mask:0xf bound_ctrl:1
	v_pk_add_f32 v[28:29], v[28:29], v[32:33]
	v_pk_add_f32 v[30:31], v[30:31], v[34:35]
	s_waitcnt vmcnt(32)
	v_cvt_f32_f16_e32 v50, v50
	v_mov_b32_dpp v33, v29 row_mirror row_mask:0xf bank_mask:0xf bound_ctrl:1
	v_mov_b32_dpp v32, v28 row_mirror row_mask:0xf bank_mask:0xf bound_ctrl:1
	s_waitcnt vmcnt(31)
	v_cvt_f32_f16_e32 v36, v36
	s_waitcnt vmcnt(30)
	v_cvt_f32_f16_e32 v37, v37
	v_mov_b32_dpp v35, v31 row_mirror row_mask:0xf bank_mask:0xf bound_ctrl:1
	v_mov_b32_dpp v34, v30 row_mirror row_mask:0xf bank_mask:0xf bound_ctrl:1
	v_pk_add_f32 v[28:29], v[28:29], v[32:33]
	v_pk_add_f32 v[30:31], v[30:31], v[34:35]
	ds_bpermute_b32 v33, v24, v29
	ds_bpermute_b32 v32, v24, v28
	s_waitcnt vmcnt(28)
	v_cvt_f32_f16_e32 v38, v38
	s_waitcnt vmcnt(27)
	v_cvt_f32_f16_e32 v39, v39
	s_waitcnt vmcnt(26)
	v_cvt_f32_f16_e32 v41, v41
	s_waitcnt vmcnt(25)
	v_cvt_f32_f16_e32 v42, v42
	s_waitcnt vmcnt(24)
	v_cvt_f32_f16_e32 v43, v43
	s_waitcnt vmcnt(23)
	v_cvt_f32_f16_e32 v51, v51
	ds_bpermute_b32 v35, v24, v31
	ds_bpermute_b32 v34, v24, v30
	v_mul_f32_e32 v36, v36, v37
	v_mul_f32_e32 v37, v17, v36
	v_mul_f32_e32 v38, v38, v39
	v_mul_f32_e32 v39, v41, v42
	v_mul_f32_e32 v41, v43, v51
	v_mov_b32_dpp v37, v37 quad_perm:[1,0,3,2] row_mask:0xf bank_mask:0xf bound_ctrl:1
	v_mul_f32_e32 v42, v19, v38
	s_waitcnt lgkmcnt(2)
	v_pk_add_f32 v[28:29], v[28:29], v[32:33]
	v_mul_f32_e32 v43, v21, v39
	v_mul_f32_e32 v51, v23, v41
	v_fmac_f32_e32 v37, v17, v36
	v_mov_b32_dpp v36, v42 quad_perm:[1,0,3,2] row_mask:0xf bank_mask:0xf bound_ctrl:1
	s_waitcnt lgkmcnt(0)
	v_pk_add_f32 v[30:31], v[30:31], v[34:35]
	ds_bpermute_b32 v33, v25, v29
	ds_bpermute_b32 v32, v25, v28
	v_mov_b32_dpp v42, v43 quad_perm:[1,0,3,2] row_mask:0xf bank_mask:0xf bound_ctrl:1
	v_mov_b32_dpp v43, v51 quad_perm:[1,0,3,2] row_mask:0xf bank_mask:0xf bound_ctrl:1
	v_fmac_f32_e32 v36, v19, v38
	ds_bpermute_b32 v35, v25, v31
	ds_bpermute_b32 v34, v25, v30
	v_add_f32_dpp v37, v37, v37 quad_perm:[2,3,0,1] row_mask:0xf bank_mask:0xf bound_ctrl:1
	v_fmac_f32_e32 v42, v21, v39
	v_fmac_f32_e32 v43, v23, v41
	v_add_f32_dpp v36, v36, v36 quad_perm:[2,3,0,1] row_mask:0xf bank_mask:0xf bound_ctrl:1
	v_add_f32_dpp v37, v37, v37 row_half_mirror row_mask:0xf bank_mask:0xf bound_ctrl:1
	v_add_f32_dpp v38, v42, v42 quad_perm:[2,3,0,1] row_mask:0xf bank_mask:0xf bound_ctrl:1
	v_add_f32_dpp v39, v43, v43 quad_perm:[2,3,0,1] row_mask:0xf bank_mask:0xf bound_ctrl:1
	v_add_f32_dpp v36, v36, v36 row_half_mirror row_mask:0xf bank_mask:0xf bound_ctrl:1
	v_add_f32_dpp v37, v37, v37 row_mirror row_mask:0xf bank_mask:0xf bound_ctrl:1
	v_add_f32_dpp v38, v38, v38 row_half_mirror row_mask:0xf bank_mask:0xf bound_ctrl:1
	v_add_f32_dpp v39, v39, v39 row_half_mirror row_mask:0xf bank_mask:0xf bound_ctrl:1
	v_add_f32_dpp v36, v36, v36 row_mirror row_mask:0xf bank_mask:0xf bound_ctrl:1
	ds_bpermute_b32 v41, v24, v37
	v_add_f32_dpp v38, v38, v38 row_mirror row_mask:0xf bank_mask:0xf bound_ctrl:1
	v_add_f32_dpp v39, v39, v39 row_mirror row_mask:0xf bank_mask:0xf bound_ctrl:1
	ds_bpermute_b32 v42, v24, v36
	s_waitcnt lgkmcnt(4)
	v_pk_add_f32 v[28:29], v[28:29], v[32:33]
	ds_bpermute_b32 v43, v24, v38
	ds_bpermute_b32 v51, v24, v39
	s_waitcnt lgkmcnt(4)
	v_pk_add_f32 v[30:31], v[30:31], v[34:35]
	v_pk_fma_f32 v[28:29], v[28:29], s[16:17], v[44:45] op_sel_hi:[1,0,1] neg_lo:[1,0,0] neg_hi:[1,0,0]
	v_pk_fma_f32 v[30:31], v[30:31], s[16:17], v[46:47] op_sel_hi:[1,0,1] neg_lo:[1,0,0] neg_hi:[1,0,0]
	v_pk_mul_f32 v[32:33], v[28:29], v[28:29]
	v_pk_mul_f32 v[34:35], v[30:31], v[30:31]
	s_waitcnt lgkmcnt(3)
	v_add_f32_e32 v41, v37, v41
	v_mov_b32_dpp v33, v33 quad_perm:[1,0,3,2] row_mask:0xf bank_mask:0xf bound_ctrl:1
	v_mov_b32_dpp v32, v32 quad_perm:[1,0,3,2] row_mask:0xf bank_mask:0xf bound_ctrl:1
	v_mov_b32_dpp v35, v35 quad_perm:[1,0,3,2] row_mask:0xf bank_mask:0xf bound_ctrl:1
	v_mov_b32_dpp v34, v34 quad_perm:[1,0,3,2] row_mask:0xf bank_mask:0xf bound_ctrl:1
	v_pk_fma_f32 v[32:33], v[28:29], v[28:29], v[32:33]
	s_waitcnt lgkmcnt(2)
	v_add_f32_e32 v42, v36, v42
	v_pk_fma_f32 v[34:35], v[30:31], v[30:31], v[34:35]
	v_mov_b32_dpp v37, v33 quad_perm:[2,3,0,1] row_mask:0xf bank_mask:0xf bound_ctrl:1
	v_mov_b32_dpp v36, v32 quad_perm:[2,3,0,1] row_mask:0xf bank_mask:0xf bound_ctrl:1
	s_waitcnt lgkmcnt(1)
	v_add_f32_e32 v43, v38, v43
	s_waitcnt lgkmcnt(0)
	v_add_f32_e32 v45, v39, v51
	v_mov_b32_dpp v39, v35 quad_perm:[2,3,0,1] row_mask:0xf bank_mask:0xf bound_ctrl:1
	v_mov_b32_dpp v38, v34 quad_perm:[2,3,0,1] row_mask:0xf bank_mask:0xf bound_ctrl:1
	v_pk_add_f32 v[32:33], v[32:33], v[36:37]
	v_pk_add_f32 v[34:35], v[34:35], v[38:39]
	ds_bpermute_b32 v44, v25, v41
	v_mov_b32_dpp v37, v33 row_half_mirror row_mask:0xf bank_mask:0xf bound_ctrl:1
	v_mov_b32_dpp v36, v32 row_half_mirror row_mask:0xf bank_mask:0xf bound_ctrl:1
	v_mov_b32_dpp v39, v35 row_half_mirror row_mask:0xf bank_mask:0xf bound_ctrl:1
	v_mov_b32_dpp v38, v34 row_half_mirror row_mask:0xf bank_mask:0xf bound_ctrl:1
	v_pk_add_f32 v[32:33], v[32:33], v[36:37]
	v_pk_add_f32 v[34:35], v[34:35], v[38:39]
	ds_bpermute_b32 v46, v25, v42
	v_mov_b32_dpp v37, v33 row_mirror row_mask:0xf bank_mask:0xf bound_ctrl:1
	v_mov_b32_dpp v36, v32 row_mirror row_mask:0xf bank_mask:0xf bound_ctrl:1
	v_mov_b32_dpp v39, v35 row_mirror row_mask:0xf bank_mask:0xf bound_ctrl:1
	v_mov_b32_dpp v38, v34 row_mirror row_mask:0xf bank_mask:0xf bound_ctrl:1
	v_pk_add_f32 v[32:33], v[32:33], v[36:37]
	v_pk_add_f32 v[34:35], v[34:35], v[38:39]
	ds_bpermute_b32 v37, v24, v33
	ds_bpermute_b32 v36, v24, v32
	ds_bpermute_b32 v39, v24, v35
	ds_bpermute_b32 v38, v24, v34
	ds_bpermute_b32 v47, v25, v43
	ds_bpermute_b32 v51, v25, v45
	s_waitcnt lgkmcnt(4)
	v_pk_add_f32 v[32:33], v[32:33], v[36:37]
	ds_bpermute_b32 v37, v25, v33
	s_waitcnt lgkmcnt(3)
	v_pk_add_f32 v[34:35], v[34:35], v[38:39]
	ds_bpermute_b32 v36, v25, v32
	ds_bpermute_b32 v39, v25, v35
	ds_bpermute_b32 v38, v25, v34
	v_add_f32_e32 v41, v41, v44
	v_add_f32_e32 v42, v42, v46
	s_waitcnt lgkmcnt(2)
	v_pk_add_f32 v[32:33], v[32:33], v[36:37]
	v_add_f32_e32 v43, v43, v47
	s_waitcnt lgkmcnt(0)
	v_pk_add_f32 v[34:35], v[34:35], v[38:39]
	v_pk_fma_f32 v[32:33], v[32:33], s[16:17], v[12:13] op_sel_hi:[1,0,0]
	v_pk_fma_f32 v[34:35], v[34:35], s[16:17], v[12:13] op_sel_hi:[1,0,0]
	v_mul_f32_e32 v36, 0x4b800000, v33
	v_cmp_gt_f32_e64 s[8:9], s3, v33
	v_mul_f32_e32 v37, 0x4b800000, v32
	v_cmp_gt_f32_e32 vcc, s3, v32
	v_mul_f32_e32 v38, 0x4b800000, v35
	v_mul_f32_e32 v39, 0x4b800000, v34
	v_cmp_gt_f32_e64 s[4:5], s3, v34
	v_cmp_gt_f32_e64 s[6:7], s3, v35
	v_cndmask_b32_e64 v33, v33, v36, s[8:9]
	v_cndmask_b32_e32 v32, v32, v37, vcc
	v_cndmask_b32_e64 v35, v35, v38, s[6:7]
	v_cndmask_b32_e64 v34, v34, v39, s[4:5]
	v_rsq_f32_e32 v33, v33
	v_rsq_f32_e32 v32, v32
	v_rsq_f32_e32 v35, v35
	v_rsq_f32_e32 v34, v34
	v_mul_f32_e32 v36, 0x45800000, v33
	v_mul_f32_e32 v37, 0x45800000, v32
	v_mul_f32_e32 v38, 0x45800000, v35
	v_mul_f32_e32 v39, 0x45800000, v34
	v_cndmask_b32_e64 v33, v33, v36, s[8:9]
	v_cndmask_b32_e32 v32, v32, v37, vcc
	v_cndmask_b32_e64 v35, v35, v38, s[6:7]
	v_cndmask_b32_e64 v34, v34, v39, s[4:5]
	v_mul_f32_e32 v29, v29, v33
	v_mul_f32_e32 v28, v28, v32
	v_mul_f32_e32 v31, v31, v35
	v_mul_f32_e32 v30, v30, v34
	v_fma_f32 v29, v16, v29, v1
	v_add_f32_e32 v44, v45, v51
	v_fma_f32 v28, v18, v28, v3
	v_fma_f32 v31, v20, v31, v5
	v_fma_f32 v30, v22, v30, v7
	v_fma_mix_f32 v29, v41, v40, v29 op_sel_hi:[0,1,0]
	s_waitcnt vmcnt(22)
	v_fma_mix_f32 v28, v42, v52, v28 op_sel_hi:[0,1,0]
	s_waitcnt vmcnt(21)
	v_fma_mix_f32 v31, v43, v53, v31 op_sel_hi:[0,1,0]
	s_waitcnt vmcnt(20)
	v_fma_mix_f32 v30, v44, v54, v30 op_sel_hi:[0,1,0]
	v_mul_f32_e32 v27, v29, v27
	v_mul_f32_e32 v28, v28, v48
	v_mul_f32_e32 v29, v31, v49
	v_mul_f32_e32 v30, v30, v50
	v_bfe_u32 v31, v27, 16, 1
	v_bfe_u32 v32, v28, 16, 1
	v_bfe_u32 v33, v29, 16, 1
	v_bfe_u32 v34, v30, 16, 1
	v_add3_u32 v27, v27, v31, s17
	v_add3_u32 v28, v28, v32, s17
	v_add3_u32 v29, v29, v33, s17
	v_add3_u32 v30, v30, v34, s17
	global_store_short_d16_hi v[14:15], v27, off offset:1024
	global_store_short_d16_hi v[14:15], v28, off offset:1152
	global_store_short_d16_hi v[14:15], v29, off offset:1280
	global_store_short_d16_hi v[14:15], v30, off offset:1408
	s_cbranch_scc1 .LBB0_1148
